# barrier: issue L1 invalidate (buffer_inv sc1) before the spin wait instead of after it (followers at arrival, leader right after TOP atomic)
# speedup vs baseline: 1.0485x; 1.0213x over previous
; __device__ __forceinline__ unsigned xb_add(unsigned* p, unsigned v) { return __hip_atomic_fetch_add(p, v, __ATOMIC_RELAXED, __HIP_MEMORY_SCOPE_AGENT); }
; __device__ __forceinline__ void grid_barrier1(int wid_s, unsigned* bar, volatile unsigned* st) {
;     ...
;             __builtin_amdgcn_fence(__ATOMIC_ACQUIRE, "agent");
;             xb_add(&bar[XB_XGEN(x)], 1u);
;             asm volatile("s_waitcnt vmcnt(0)" ::: "memory");
.LBB0_424:
	s_or_b64 exec, exec, s[2:3]
	v_mov_b32_e32 v0, s25
	v_add_co_u32_e32 v0, vcc, 0x2000, v0
	v_mov_b32_e32 v1, s24
	s_nop 0
	v_addc_co_u32_e32 v1, vcc, 0, v1, vcc
	s_waitcnt vmcnt(0) lgkmcnt(0)
	flat_atomic_add v[0:1], v170 offset:1024
	s_waitcnt vmcnt(0)

; __device__ __forceinline__ unsigned xb_ld(unsigned* p)              { return __hip_atomic_load(p, __ATOMIC_RELAXED, __HIP_MEMORY_SCOPE_AGENT); }
; __device__ __forceinline__ unsigned xb_add(unsigned* p, unsigned v) { return __hip_atomic_fetch_add(p, v, __ATOMIC_RELAXED, __HIP_MEMORY_SCOPE_AGENT); }
; #define XB_SPIN(cond, bar) do { unsigned _sp = 0; while (cond) { \
;     if ((++_sp & 255u) == 0u) { if (xb_ld(&(bar)[XB_TMO])) break; if (_sp > XB_SPIN_CAP) { atomicAdd(&(bar)[XB_TMO], 1u); break; } } } } while (0)
; __device__ __forceinline__ void grid_barrier1(int wid_s, unsigned* bar, volatile unsigned* st) {
;     ...
;         const unsigned old = xb_add(&bar[XB_XSUB(x)], 1u);
;         const unsigned gen = old / nloc;
;         if (old + 1u == (gen + 1u) * nloc) {
;     ...
;         } else {
;             XB_SPIN(xb_ld(&bar[XB_XGEN(x)]) == gen, bar);
;             __builtin_amdgcn_fence(__ATOMIC_ACQUIRE, "agent");
.LBB0_441:
	s_or_b64 exec, exec, s[44:45]
	s_lshl_b32 s2, s33, 8
	s_add_u32 s25, s92, s2
	s_addc_u32 s24, s94, 0
	v_mov_b32_e32 v1, s25
	v_add_co_u32_e32 v4, vcc, 0x1000, v1
	v_mov_b32_e32 v1, s24
	s_nop 0
	v_addc_co_u32_e32 v5, vcc, 0, v1, vcc
	flat_atomic_add v1, v[4:5], v170 offset:1024 sc0
	v_cvt_f32_u32_e32 v3, v2
	v_sub_u32_e32 v4, 0, v2
	v_rcp_iflag_f32_e32 v3, v3
	s_nop 0
	v_mul_f32_e32 v3, 0x4f7ffffe, v3
	v_cvt_u32_f32_e32 v3, v3
	v_mul_lo_u32 v4, v4, v3
	v_mul_hi_u32 v4, v3, v4
	v_add_u32_e32 v3, v3, v4
	s_waitcnt vmcnt(0) lgkmcnt(0)
	v_mul_hi_u32 v3, v1, v3
	v_mul_lo_u32 v5, v3, v2
	v_add_u32_e32 v4, 1, v1
	v_sub_u32_e32 v1, v1, v5
	v_add_u32_e32 v6, 1, v3
	v_cmp_ge_u32_e32 vcc, v1, v2
	v_sub_u32_e32 v5, v1, v2
	s_nop 0
	v_cndmask_b32_e32 v3, v3, v6, vcc
	v_cndmask_b32_e32 v1, v1, v5, vcc
	v_add_u32_e32 v5, 1, v3
	v_cmp_ge_u32_e32 vcc, v1, v2
	s_nop 1
	v_cndmask_b32_e32 v1, v3, v5, vcc
	v_mad_u64_u32 v[2:3], s[2:3], v2, v1, v[2:3]
	v_cmp_ne_u32_e32 vcc, v4, v2
	s_and_saveexec_b64 s[2:3], vcc
	s_xor_b64 s[2:3], exec, s[2:3]
	s_movk_i32 s33, 0x300
	s_cbranch_execz .LBB0_454
	buffer_inv sc1
	v_mov_b32_e32 v0, s25
	v_add_co_u32_e32 v2, vcc, 0x2000, v0
	v_mov_b32_e32 v0, s24
	s_nop 0
	v_addc_co_u32_e32 v3, vcc, 0, v0, vcc
	flat_load_dword v0, v[2:3] offset:1024 sc1
	s_add_u32 s6, s25, 0x2400
	s_addc_u32 s7, s24, 0
	s_waitcnt vmcnt(0) lgkmcnt(0)
	v_cmp_eq_u32_e32 vcc, v0, v1
	s_and_saveexec_b64 s[4:5], vcc
	s_cbranch_execz .LBB0_453
	s_mov_b32 s26, 1
	s_mov_b64 s[8:9], 0
	s_branch .LBB0_445

; __device__ __forceinline__ unsigned xb_ld(unsigned* p)              { return __hip_atomic_load(p, __ATOMIC_RELAXED, __HIP_MEMORY_SCOPE_AGENT); }
; __device__ __forceinline__ unsigned xb_add(unsigned* p, unsigned v) { return __hip_atomic_fetch_add(p, v, __ATOMIC_RELAXED, __HIP_MEMORY_SCOPE_AGENT); }
; #define XB_SPIN(cond, bar) do { unsigned _sp = 0; while (cond) { \
;     if ((++_sp & 255u) == 0u) { if (xb_ld(&(bar)[XB_TMO])) break; if (_sp > XB_SPIN_CAP) { atomicAdd(&(bar)[XB_TMO], 1u); break; } } } } while (0)
; __device__ __forceinline__ void grid_barrier1(int wid_s, unsigned* bar, volatile unsigned* st) {
;     ...
;             __builtin_amdgcn_fence(__ATOMIC_RELEASE, "agent");
;             asm volatile("s_waitcnt vmcnt(0)" ::: "memory");
;             const unsigned og = xb_add(&bar[XB_TOP], 1u);
;             const unsigned tg = og / nx;
;             if (og + 1u == (tg + 1u) * nx) xb_add(&bar[XB_TOPGEN], 1u);
;             else XB_SPIN(xb_ld(&bar[XB_TOPGEN]) == tg, bar);
;             __builtin_amdgcn_fence(__ATOMIC_ACQUIRE, "agent");
;             xb_add(&bar[XB_XGEN(x)], 1u);
;             asm volatile("s_waitcnt vmcnt(0)" ::: "memory");
;         } else {
;             XB_SPIN(xb_ld(&bar[XB_XGEN(x)]) == gen, bar);
;             __builtin_amdgcn_fence(__ATOMIC_ACQUIRE, "agent");
;             asm volatile("s_waitcnt vmcnt(0)" ::: "memory");
.LBB0_453:
	s_or_b64 exec, exec, s[4:5]
	s_waitcnt vmcnt(0) lgkmcnt(0)
	s_waitcnt vmcnt(0)
.LBB0_454:
	s_andn2_saveexec_b64 s[2:3], s[2:3]
	s_cbranch_execz .LBB0_425
	v_readlane_b32 s2, v254, 15
	v_readlane_b32 s3, v254, 16
	buffer_wbl2 sc1
	s_waitcnt vmcnt(0)
	s_mov_b64 s[4:5], -1
	v_mov_b64_e32 v[2:3], s[2:3]
	flat_atomic_add v1, v[2:3], v170 sc0
	buffer_inv sc1
	v_cvt_f32_u32_e32 v2, v0
	v_sub_u32_e32 v3, 0, v0
	v_rcp_iflag_f32_e32 v2, v2
	s_nop 0
	v_mul_f32_e32 v2, 0x4f7ffffe, v2
	v_cvt_u32_f32_e32 v2, v2
	v_mul_lo_u32 v3, v3, v2
	v_mul_hi_u32 v3, v2, v3
	v_add_u32_e32 v2, v2, v3
	s_waitcnt vmcnt(0) lgkmcnt(0)
	v_mul_hi_u32 v2, v1, v2
	v_mul_lo_u32 v4, v2, v0
	v_add_u32_e32 v3, 1, v1
	v_sub_u32_e32 v1, v1, v4
	v_add_u32_e32 v5, 1, v2
	v_cmp_ge_u32_e32 vcc, v1, v0
	v_sub_u32_e32 v4, v1, v0
	s_nop 0
	v_cndmask_b32_e32 v2, v2, v5, vcc
	v_cndmask_b32_e32 v1, v1, v4, vcc
	v_add_u32_e32 v4, 1, v2
	v_cmp_ge_u32_e32 vcc, v1, v0
	s_nop 1
	v_cndmask_b32_e32 v2, v2, v4, vcc
	v_mad_u64_u32 v[0:1], s[2:3], v0, v2, v[0:1]
	v_readlane_b32 s2, v254, 19
	v_readlane_b32 s3, v254, 20
	v_cmp_ne_u32_e32 vcc, v3, v0
	s_nop 0
	v_mov_b64_e32 v[0:1], s[2:3]
	s_and_saveexec_b64 s[2:3], vcc
	s_cbranch_execz .LBB0_467
	v_readlane_b32 s4, v254, 19
	v_readlane_b32 s5, v254, 20
	s_mov_b64 s[6:7], 0
	s_nop 0
	v_mov_b64_e32 v[0:1], s[4:5]
	flat_load_dword v0, v[0:1] sc1
	s_waitcnt vmcnt(0) lgkmcnt(0)
	v_cmp_eq_u32_e32 vcc, v0, v2
	s_and_saveexec_b64 s[4:5], vcc
	s_cbranch_execz .LBB0_466
	s_mov_b32 s20, 1
	s_branch .LBB0_459

; __device__ __forceinline__ unsigned xb_ld(unsigned* p)              { return __hip_atomic_load(p, __ATOMIC_RELAXED, __HIP_MEMORY_SCOPE_AGENT); }
; __device__ __forceinline__ unsigned xb_add(unsigned* p, unsigned v) { return __hip_atomic_fetch_add(p, v, __ATOMIC_RELAXED, __HIP_MEMORY_SCOPE_AGENT); }
; #define XB_SPIN(cond, bar) do { unsigned _sp = 0; while (cond) { \
;     if ((++_sp & 255u) == 0u) { if (xb_ld(&(bar)[XB_TMO])) break; if (_sp > XB_SPIN_CAP) { atomicAdd(&(bar)[XB_TMO], 1u); break; } } } } while (0)
; __device__ __forceinline__ void grid_barrier1(int wid_s, unsigned* bar, volatile unsigned* st) {
;     ...
;         const unsigned old = xb_add(&bar[XB_XSUB(x)], 1u);
;         const unsigned gen = old / nloc;
;         if (old + 1u == (gen + 1u) * nloc) {
;     ...
;         } else {
;             XB_SPIN(xb_ld(&bar[XB_XGEN(x)]) == gen, bar);
;             __builtin_amdgcn_fence(__ATOMIC_ACQUIRE, "agent");
.LBB0_975:
	s_or_b64 exec, exec, s[56:57]
	s_lshl_b32 s2, s33, 8
	s_add_u32 s25, s92, s2
	s_addc_u32 s24, s94, 0
	v_mov_b32_e32 v1, s25
	v_add_co_u32_e32 v4, vcc, 0x1000, v1
	v_mov_b32_e32 v1, s24
	s_nop 0
	v_addc_co_u32_e32 v5, vcc, 0, v1, vcc
	flat_atomic_add v3, v[4:5], v170 offset:1024 sc0
	v_cvt_f32_u32_e32 v1, v2
	v_sub_u32_e32 v4, 0, v2
	v_rcp_iflag_f32_e32 v1, v1
	s_nop 0
	v_mul_f32_e32 v1, 0x4f7ffffe, v1
	v_cvt_u32_f32_e32 v1, v1
	v_mul_lo_u32 v4, v4, v1
	v_mul_hi_u32 v4, v1, v4
	v_add_u32_e32 v1, v1, v4
	s_waitcnt vmcnt(0) lgkmcnt(0)
	v_mul_hi_u32 v1, v3, v1
	v_mul_lo_u32 v4, v1, v2
	v_sub_u32_e32 v4, v3, v4
	v_cmp_ge_u32_e32 vcc, v4, v2
	v_add_u32_e32 v5, 1, v1
	s_nop 0
	v_cndmask_b32_e32 v1, v1, v5, vcc
	v_sub_u32_e32 v5, v4, v2
	v_cndmask_b32_e32 v4, v4, v5, vcc
	v_cmp_ge_u32_e32 vcc, v4, v2
	v_add_u32_e32 v4, 1, v1
	s_nop 0
	v_cndmask_b32_e32 v1, v1, v4, vcc
	v_add_u32_e32 v4, 1, v3
	v_mad_u64_u32 v[2:3], s[2:3], v2, v1, v[2:3]
	v_cmp_ne_u32_e32 vcc, v4, v2
	s_and_saveexec_b64 s[2:3], vcc
	s_xor_b64 s[2:3], exec, s[2:3]
	s_movk_i32 s33, 0x300
	s_cbranch_execz .LBB0_988
	buffer_inv sc1
	v_mov_b32_e32 v0, s25
	v_add_co_u32_e32 v2, vcc, 0x2000, v0
	v_mov_b32_e32 v0, s24
	s_nop 0
	v_addc_co_u32_e32 v3, vcc, 0, v0, vcc
	flat_load_dword v0, v[2:3] offset:1024 sc1
	s_add_u32 s6, s25, 0x2400
	s_addc_u32 s7, s24, 0
	s_waitcnt vmcnt(0) lgkmcnt(0)
	v_cmp_eq_u32_e32 vcc, v0, v1
	s_and_saveexec_b64 s[4:5], vcc
	s_cbranch_execz .LBB0_987
	s_mov_b32 s26, 1
	s_mov_b64 s[8:9], 0
	s_branch .LBB0_979

; __device__ __forceinline__ unsigned xb_ld(unsigned* p)              { return __hip_atomic_load(p, __ATOMIC_RELAXED, __HIP_MEMORY_SCOPE_AGENT); }
; __device__ __forceinline__ unsigned xb_add(unsigned* p, unsigned v) { return __hip_atomic_fetch_add(p, v, __ATOMIC_RELAXED, __HIP_MEMORY_SCOPE_AGENT); }
; #define XB_SPIN(cond, bar) do { unsigned _sp = 0; while (cond) { \
;     if ((++_sp & 255u) == 0u) { if (xb_ld(&(bar)[XB_TMO])) break; if (_sp > XB_SPIN_CAP) { atomicAdd(&(bar)[XB_TMO], 1u); break; } } } } while (0)
; __device__ __forceinline__ void grid_barrier1(int wid_s, unsigned* bar, volatile unsigned* st) {
;     ...
;             __builtin_amdgcn_fence(__ATOMIC_RELEASE, "agent");
;             asm volatile("s_waitcnt vmcnt(0)" ::: "memory");
;             const unsigned og = xb_add(&bar[XB_TOP], 1u);
;             const unsigned tg = og / nx;
;             if (og + 1u == (tg + 1u) * nx) xb_add(&bar[XB_TOPGEN], 1u);
;             else XB_SPIN(xb_ld(&bar[XB_TOPGEN]) == tg, bar);
.LBB0_988:
	s_andn2_saveexec_b64 s[2:3], s[2:3]
	s_cbranch_execz .LBB0_959
	v_readlane_b32 s2, v254, 15
	v_readlane_b32 s3, v254, 16
	buffer_wbl2 sc1
	s_waitcnt vmcnt(0)
	s_mov_b64 s[4:5], -1
	v_mov_b64_e32 v[2:3], s[2:3]
	flat_atomic_add v1, v[2:3], v170 sc0
	buffer_inv sc1
	v_cvt_f32_u32_e32 v2, v0
	v_sub_u32_e32 v3, 0, v0
	v_rcp_iflag_f32_e32 v2, v2
	s_nop 0
	v_mul_f32_e32 v2, 0x4f7ffffe, v2
	v_cvt_u32_f32_e32 v2, v2
	v_mul_lo_u32 v3, v3, v2
	v_mul_hi_u32 v3, v2, v3
	v_add_u32_e32 v2, v2, v3
	s_waitcnt vmcnt(0) lgkmcnt(0)
	v_mul_hi_u32 v2, v1, v2
	v_mul_lo_u32 v3, v2, v0
	v_sub_u32_e32 v3, v1, v3
	v_cmp_ge_u32_e32 vcc, v3, v0
	v_add_u32_e32 v4, 1, v2
	s_nop 0
	v_cndmask_b32_e32 v2, v2, v4, vcc
	v_sub_u32_e32 v4, v3, v0
	v_cndmask_b32_e32 v3, v3, v4, vcc
	v_cmp_ge_u32_e32 vcc, v3, v0
	v_add_u32_e32 v3, 1, v2
	s_nop 0
	v_cndmask_b32_e32 v2, v2, v3, vcc
	v_add_u32_e32 v3, 1, v1
	v_mad_u64_u32 v[0:1], s[2:3], v0, v2, v[0:1]
	v_readlane_b32 s2, v254, 19
	v_readlane_b32 s3, v254, 20
	v_cmp_ne_u32_e32 vcc, v3, v0
	s_nop 0
	v_mov_b64_e32 v[0:1], s[2:3]
	s_and_saveexec_b64 s[2:3], vcc
	s_cbranch_execz .LBB0_1001
	v_readlane_b32 s4, v254, 19
	v_readlane_b32 s5, v254, 20
	s_mov_b64 s[6:7], 0
	s_nop 0
	v_mov_b64_e32 v[0:1], s[4:5]
	flat_load_dword v0, v[0:1] sc1
	s_waitcnt vmcnt(0) lgkmcnt(0)
	v_cmp_eq_u32_e32 vcc, v0, v2
	s_and_saveexec_b64 s[4:5], vcc
	s_cbranch_execz .LBB0_1000
	s_mov_b32 s20, 1
	s_branch .LBB0_993

; __device__ __forceinline__ unsigned xb_add(unsigned* p, unsigned v) { return __hip_atomic_fetch_add(p, v, __ATOMIC_RELAXED, __HIP_MEMORY_SCOPE_AGENT); }
; __device__ __forceinline__ void grid_barrier1(int wid_s, unsigned* bar, volatile unsigned* st) {
;     ...
;             __builtin_amdgcn_fence(__ATOMIC_ACQUIRE, "agent");
;             xb_add(&bar[XB_XGEN(x)], 1u);
;             asm volatile("s_waitcnt vmcnt(0)" ::: "memory");
.LBB0_1167:
	s_or_b64 exec, exec, s[2:3]
	v_mov_b32_e32 v0, s24
	v_add_co_u32_e32 v0, vcc, 0x2000, v0
	v_mov_b32_e32 v1, s19
	s_nop 0
	v_addc_co_u32_e32 v1, vcc, 0, v1, vcc
	s_waitcnt vmcnt(0) lgkmcnt(0)
	flat_atomic_add v[0:1], v170 offset:1024
	s_waitcnt vmcnt(0)

; __device__ __forceinline__ unsigned xb_ld(unsigned* p)              { return __hip_atomic_load(p, __ATOMIC_RELAXED, __HIP_MEMORY_SCOPE_AGENT); }
; __device__ __forceinline__ unsigned xb_add(unsigned* p, unsigned v) { return __hip_atomic_fetch_add(p, v, __ATOMIC_RELAXED, __HIP_MEMORY_SCOPE_AGENT); }
; #define XB_SPIN(cond, bar) do { unsigned _sp = 0; while (cond) { \
;     if ((++_sp & 255u) == 0u) { if (xb_ld(&(bar)[XB_TMO])) break; if (_sp > XB_SPIN_CAP) { atomicAdd(&(bar)[XB_TMO], 1u); break; } } } } while (0)
; __device__ __forceinline__ void grid_barrier1(int wid_s, unsigned* bar, volatile unsigned* st) {
;     ...
;         const unsigned old = xb_add(&bar[XB_XSUB(x)], 1u);
;         const unsigned gen = old / nloc;
;         if (old + 1u == (gen + 1u) * nloc) {
;     ...
;         } else {
;             XB_SPIN(xb_ld(&bar[XB_XGEN(x)]) == gen, bar);
;             __builtin_amdgcn_fence(__ATOMIC_ACQUIRE, "agent");
.LBB0_1184:
	s_or_b64 exec, exec, s[46:47]
	s_lshl_b32 s2, s19, 8
	s_add_u32 s24, s92, s2
	s_addc_u32 s19, s94, 0
	v_mov_b32_e32 v1, s24
	v_add_co_u32_e32 v4, vcc, 0x1000, v1
	v_mov_b32_e32 v1, s19
	s_nop 0
	v_addc_co_u32_e32 v5, vcc, 0, v1, vcc
	flat_atomic_add v3, v[4:5], v170 offset:1024 sc0
	v_cvt_f32_u32_e32 v1, v2
	v_sub_u32_e32 v4, 0, v2
	v_rcp_iflag_f32_e32 v1, v1
	s_nop 0
	v_mul_f32_e32 v1, 0x4f7ffffe, v1
	v_cvt_u32_f32_e32 v1, v1
	v_mul_lo_u32 v4, v4, v1
	v_mul_hi_u32 v4, v1, v4
	v_add_u32_e32 v1, v1, v4
	s_waitcnt vmcnt(0) lgkmcnt(0)
	v_mul_hi_u32 v1, v3, v1
	v_mul_lo_u32 v4, v1, v2
	v_sub_u32_e32 v4, v3, v4
	v_cmp_ge_u32_e32 vcc, v4, v2
	v_add_u32_e32 v5, 1, v1
	s_nop 0
	v_cndmask_b32_e32 v1, v1, v5, vcc
	v_sub_u32_e32 v5, v4, v2
	v_cndmask_b32_e32 v4, v4, v5, vcc
	v_cmp_ge_u32_e32 vcc, v4, v2
	v_add_u32_e32 v4, 1, v1
	s_nop 0
	v_cndmask_b32_e32 v1, v1, v4, vcc
	v_add_u32_e32 v4, 1, v3
	v_mad_u64_u32 v[2:3], s[2:3], v2, v1, v[2:3]
	v_cmp_ne_u32_e32 vcc, v4, v2
	s_and_saveexec_b64 s[2:3], vcc
	s_xor_b64 s[2:3], exec, s[2:3]
	s_movk_i32 s33, 0x300
	s_cbranch_execz .LBB0_1197
	buffer_inv sc1
	v_mov_b32_e32 v0, s24
	v_add_co_u32_e32 v2, vcc, 0x2000, v0
	v_mov_b32_e32 v0, s19
	s_nop 0
	v_addc_co_u32_e32 v3, vcc, 0, v0, vcc
	flat_load_dword v0, v[2:3] offset:1024 sc1
	s_add_u32 s6, s24, 0x2400
	s_addc_u32 s7, s19, 0
	s_waitcnt vmcnt(0) lgkmcnt(0)
	v_cmp_eq_u32_e32 vcc, v0, v1
	s_and_saveexec_b64 s[4:5], vcc
	s_cbranch_execz .LBB0_1196
	s_mov_b32 s25, 1
	s_mov_b64 s[8:9], 0
	s_branch .LBB0_1188

; __device__ __forceinline__ unsigned xb_ld(unsigned* p)              { return __hip_atomic_load(p, __ATOMIC_RELAXED, __HIP_MEMORY_SCOPE_AGENT); }
; __device__ __forceinline__ unsigned xb_add(unsigned* p, unsigned v) { return __hip_atomic_fetch_add(p, v, __ATOMIC_RELAXED, __HIP_MEMORY_SCOPE_AGENT); }
; #define XB_SPIN(cond, bar) do { unsigned _sp = 0; while (cond) { \
;     if ((++_sp & 255u) == 0u) { if (xb_ld(&(bar)[XB_TMO])) break; if (_sp > XB_SPIN_CAP) { atomicAdd(&(bar)[XB_TMO], 1u); break; } } } } while (0)
; __device__ __forceinline__ void grid_barrier1(int wid_s, unsigned* bar, volatile unsigned* st) {
;     ...
;         const unsigned old = xb_add(&bar[XB_XSUB(x)], 1u);
;         const unsigned gen = old / nloc;
;         if (old + 1u == (gen + 1u) * nloc) {
;     ...
;         } else {
;             XB_SPIN(xb_ld(&bar[XB_XGEN(x)]) == gen, bar);
;             __builtin_amdgcn_fence(__ATOMIC_ACQUIRE, "agent");
.LBB0_1256:
	s_or_b64 exec, exec, s[56:57]
	s_lshl_b32 s2, s37, 8
	s_add_u32 s25, s92, s2
	s_addc_u32 s24, s94, 0
	v_mov_b32_e32 v1, s25
	v_add_co_u32_e32 v4, vcc, 0x1000, v1
	v_mov_b32_e32 v1, s24
	s_nop 0
	v_addc_co_u32_e32 v5, vcc, 0, v1, vcc
	flat_atomic_add v3, v[4:5], v170 offset:1024 sc0
	v_cvt_f32_u32_e32 v1, v2
	v_sub_u32_e32 v4, 0, v2
	v_rcp_iflag_f32_e32 v1, v1
	s_nop 0
	v_mul_f32_e32 v1, 0x4f7ffffe, v1
	v_cvt_u32_f32_e32 v1, v1
	v_mul_lo_u32 v4, v4, v1
	v_mul_hi_u32 v4, v1, v4
	v_add_u32_e32 v1, v1, v4
	s_waitcnt vmcnt(0) lgkmcnt(0)
	v_mul_hi_u32 v1, v3, v1
	v_mul_lo_u32 v4, v1, v2
	v_sub_u32_e32 v4, v3, v4
	v_cmp_ge_u32_e32 vcc, v4, v2
	v_add_u32_e32 v5, 1, v1
	s_nop 0
	v_cndmask_b32_e32 v1, v1, v5, vcc
	v_sub_u32_e32 v5, v4, v2
	v_cndmask_b32_e32 v4, v4, v5, vcc
	v_cmp_ge_u32_e32 vcc, v4, v2
	v_add_u32_e32 v4, 1, v1
	s_nop 0
	v_cndmask_b32_e32 v1, v1, v4, vcc
	v_add_u32_e32 v4, 1, v3
	v_mad_u64_u32 v[2:3], s[2:3], v2, v1, v[2:3]
	v_cmp_ne_u32_e32 vcc, v4, v2
	s_and_saveexec_b64 s[2:3], vcc
	s_xor_b64 s[2:3], exec, s[2:3]
	s_movk_i32 s39, 0x7f
	v_readlane_b32 s40, v254, 62
	v_readlane_b32 s41, v254, 63
	s_cbranch_execz .LBB0_1269
	buffer_inv sc1
	v_mov_b32_e32 v0, s25
	v_add_co_u32_e32 v2, vcc, 0x2000, v0
	v_mov_b32_e32 v0, s24
	s_nop 0
	v_addc_co_u32_e32 v3, vcc, 0, v0, vcc
	flat_load_dword v0, v[2:3] offset:1024 sc1
	s_add_u32 s6, s25, 0x2400
	s_addc_u32 s7, s24, 0
	s_waitcnt vmcnt(0) lgkmcnt(0)
	v_cmp_eq_u32_e32 vcc, v0, v1
	s_and_saveexec_b64 s[4:5], vcc
	s_cbranch_execz .LBB0_1268
	s_mov_b32 s26, 1
	s_mov_b64 s[8:9], 0
	s_branch .LBB0_1260

; __device__ __forceinline__ unsigned xb_ld(unsigned* p)              { return __hip_atomic_load(p, __ATOMIC_RELAXED, __HIP_MEMORY_SCOPE_AGENT); }
; __device__ __forceinline__ unsigned xb_add(unsigned* p, unsigned v) { return __hip_atomic_fetch_add(p, v, __ATOMIC_RELAXED, __HIP_MEMORY_SCOPE_AGENT); }
; #define XB_SPIN(cond, bar) do { unsigned _sp = 0; while (cond) { \
;     if ((++_sp & 255u) == 0u) { if (xb_ld(&(bar)[XB_TMO])) break; if (_sp > XB_SPIN_CAP) { atomicAdd(&(bar)[XB_TMO], 1u); break; } } } } while (0)
; __device__ __forceinline__ void grid_barrier1(int wid_s, unsigned* bar, volatile unsigned* st) {
;     ...
;         const unsigned old = xb_add(&bar[XB_XSUB(x)], 1u);
;         const unsigned gen = old / nloc;
;         if (old + 1u == (gen + 1u) * nloc) {
;     ...
;         } else {
;             XB_SPIN(xb_ld(&bar[XB_XGEN(x)]) == gen, bar);
;             __builtin_amdgcn_fence(__ATOMIC_ACQUIRE, "agent");
.LBB0_1661:
	s_or_b64 exec, exec, s[52:53]
	s_lshl_b32 s2, s19, 8
	s_add_u32 s24, s92, s2
	s_addc_u32 s19, s94, 0
	v_mov_b32_e32 v1, s24
	v_add_co_u32_e32 v4, vcc, 0x1000, v1
	v_mov_b32_e32 v1, s19
	s_nop 0
	v_addc_co_u32_e32 v5, vcc, 0, v1, vcc
	flat_atomic_add v3, v[4:5], v170 offset:1024 sc0
	v_cvt_f32_u32_e32 v1, v2
	v_sub_u32_e32 v4, 0, v2
	v_rcp_iflag_f32_e32 v1, v1
	s_nop 0
	v_mul_f32_e32 v1, 0x4f7ffffe, v1
	v_cvt_u32_f32_e32 v1, v1
	v_mul_lo_u32 v4, v4, v1
	v_mul_hi_u32 v4, v1, v4
	v_add_u32_e32 v1, v1, v4
	s_waitcnt vmcnt(0) lgkmcnt(0)
	v_mul_hi_u32 v1, v3, v1
	v_mul_lo_u32 v4, v1, v2
	v_sub_u32_e32 v4, v3, v4
	v_cmp_ge_u32_e32 vcc, v4, v2
	v_add_u32_e32 v5, 1, v1
	s_nop 0
	v_cndmask_b32_e32 v1, v1, v5, vcc
	v_sub_u32_e32 v5, v4, v2
	v_cndmask_b32_e32 v4, v4, v5, vcc
	v_cmp_ge_u32_e32 vcc, v4, v2
	v_add_u32_e32 v4, 1, v1
	s_nop 0
	v_cndmask_b32_e32 v1, v1, v4, vcc
	v_add_u32_e32 v4, 1, v3
	v_mad_u64_u32 v[2:3], s[2:3], v2, v1, v[2:3]
	v_cmp_ne_u32_e32 vcc, v4, v2
	s_and_saveexec_b64 s[2:3], vcc
	s_xor_b64 s[2:3], exec, s[2:3]
	s_movk_i32 s33, 0x300
	s_cbranch_execz .LBB0_1674
	buffer_inv sc1
	v_mov_b32_e32 v0, s24
	v_add_co_u32_e32 v2, vcc, 0x2000, v0
	v_mov_b32_e32 v0, s19
	s_nop 0
	v_addc_co_u32_e32 v3, vcc, 0, v0, vcc
	flat_load_dword v0, v[2:3] offset:1024 sc1
	s_add_u32 s6, s24, 0x2400
	s_addc_u32 s7, s19, 0
	s_waitcnt vmcnt(0) lgkmcnt(0)
	v_cmp_eq_u32_e32 vcc, v0, v1
	s_and_saveexec_b64 s[4:5], vcc
	s_cbranch_execz .LBB0_1673
	s_mov_b32 s25, 1
	s_mov_b64 s[8:9], 0
	s_branch .LBB0_1665

; __device__ __forceinline__ unsigned xb_ld(unsigned* p)              { return __hip_atomic_load(p, __ATOMIC_RELAXED, __HIP_MEMORY_SCOPE_AGENT); }
; __device__ __forceinline__ unsigned xb_add(unsigned* p, unsigned v) { return __hip_atomic_fetch_add(p, v, __ATOMIC_RELAXED, __HIP_MEMORY_SCOPE_AGENT); }
; #define XB_SPIN(cond, bar) do { unsigned _sp = 0; while (cond) { \
;     if ((++_sp & 255u) == 0u) { if (xb_ld(&(bar)[XB_TMO])) break; if (_sp > XB_SPIN_CAP) { atomicAdd(&(bar)[XB_TMO], 1u); break; } } } } while (0)
; __device__ __forceinline__ void grid_barrier1(int wid_s, unsigned* bar, volatile unsigned* st) {
;     ...
;         const unsigned old = xb_add(&bar[XB_XSUB(x)], 1u);
;         const unsigned gen = old / nloc;
;         if (old + 1u == (gen + 1u) * nloc) {
;     ...
;         } else {
;             XB_SPIN(xb_ld(&bar[XB_XGEN(x)]) == gen, bar);
;             __builtin_amdgcn_fence(__ATOMIC_ACQUIRE, "agent");
.LBB0_1793:
	s_or_b64 exec, exec, s[46:47]
	s_lshl_b32 s2, s36, 8
	s_add_u32 s25, s92, s2
	s_addc_u32 s24, s94, 0
	v_mov_b32_e32 v1, s25
	v_add_co_u32_e32 v4, vcc, 0x1000, v1
	v_mov_b32_e32 v1, s24
	s_nop 0
	v_addc_co_u32_e32 v5, vcc, 0, v1, vcc
	flat_atomic_add v3, v[4:5], v170 offset:1024 sc0
	v_cvt_f32_u32_e32 v1, v2
	v_sub_u32_e32 v4, 0, v2
	v_rcp_iflag_f32_e32 v1, v1
	s_nop 0
	v_mul_f32_e32 v1, 0x4f7ffffe, v1
	v_cvt_u32_f32_e32 v1, v1
	v_mul_lo_u32 v4, v4, v1
	v_mul_hi_u32 v4, v1, v4
	v_add_u32_e32 v1, v1, v4
	s_waitcnt vmcnt(0) lgkmcnt(0)
	v_mul_hi_u32 v1, v3, v1
	v_mul_lo_u32 v4, v1, v2
	v_sub_u32_e32 v4, v3, v4
	v_cmp_ge_u32_e32 vcc, v4, v2
	v_add_u32_e32 v5, 1, v1
	s_nop 0
	v_cndmask_b32_e32 v1, v1, v5, vcc
	v_sub_u32_e32 v5, v4, v2
	v_cndmask_b32_e32 v4, v4, v5, vcc
	v_cmp_ge_u32_e32 vcc, v4, v2
	v_add_u32_e32 v4, 1, v1
	s_nop 0
	v_cndmask_b32_e32 v1, v1, v4, vcc
	v_add_u32_e32 v4, 1, v3
	v_mad_u64_u32 v[2:3], s[2:3], v2, v1, v[2:3]
	v_cmp_ne_u32_e32 vcc, v4, v2
	s_and_saveexec_b64 s[2:3], vcc
	s_xor_b64 s[2:3], exec, s[2:3]
	s_movk_i32 s39, 0x7f
	s_cbranch_execz .LBB0_1806
	buffer_inv sc1
	v_mov_b32_e32 v0, s25
	v_add_co_u32_e32 v2, vcc, 0x2000, v0
	v_mov_b32_e32 v0, s24
	s_nop 0
	v_addc_co_u32_e32 v3, vcc, 0, v0, vcc
	flat_load_dword v0, v[2:3] offset:1024 sc1
	s_add_u32 s6, s25, 0x2400
	s_addc_u32 s7, s24, 0
	s_waitcnt vmcnt(0) lgkmcnt(0)
	v_cmp_eq_u32_e32 vcc, v0, v1
	s_and_saveexec_b64 s[4:5], vcc
	s_cbranch_execz .LBB0_1805
	s_mov_b32 s26, 1
	s_mov_b64 s[8:9], 0
	s_branch .LBB0_1797

; __device__ __forceinline__ unsigned xb_ld(unsigned* p)              { return __hip_atomic_load(p, __ATOMIC_RELAXED, __HIP_MEMORY_SCOPE_AGENT); }
; __device__ __forceinline__ unsigned xb_add(unsigned* p, unsigned v) { return __hip_atomic_fetch_add(p, v, __ATOMIC_RELAXED, __HIP_MEMORY_SCOPE_AGENT); }
; #define XB_SPIN(cond, bar) do { unsigned _sp = 0; while (cond) { \
;     if ((++_sp & 255u) == 0u) { if (xb_ld(&(bar)[XB_TMO])) break; if (_sp > XB_SPIN_CAP) { atomicAdd(&(bar)[XB_TMO], 1u); break; } } } } while (0)
; __device__ __forceinline__ void grid_barrier1(int wid_s, unsigned* bar, volatile unsigned* st) {
;     ...
;         const unsigned old = xb_add(&bar[XB_XSUB(x)], 1u);
;         const unsigned gen = old / nloc;
;         if (old + 1u == (gen + 1u) * nloc) {
;     ...
;         } else {
;             XB_SPIN(xb_ld(&bar[XB_XGEN(x)]) == gen, bar);
;             __builtin_amdgcn_fence(__ATOMIC_ACQUIRE, "agent");
.LBB0_2175:
	s_or_b64 exec, exec, s[46:47]
	s_lshl_b32 s2, s37, 8
	s_add_u32 s25, s92, s2
	s_addc_u32 s24, s94, 0
	v_mov_b32_e32 v1, s25
	v_add_co_u32_e32 v4, vcc, 0x1000, v1
	v_mov_b32_e32 v1, s24
	s_nop 0
	v_addc_co_u32_e32 v5, vcc, 0, v1, vcc
	flat_atomic_add v3, v[4:5], v170 offset:1024 sc0
	v_cvt_f32_u32_e32 v1, v2
	v_sub_u32_e32 v4, 0, v2
	v_rcp_iflag_f32_e32 v1, v1
	s_nop 0
	v_mul_f32_e32 v1, 0x4f7ffffe, v1
	v_cvt_u32_f32_e32 v1, v1
	v_mul_lo_u32 v4, v4, v1
	v_mul_hi_u32 v4, v1, v4
	v_add_u32_e32 v1, v1, v4
	s_waitcnt vmcnt(0) lgkmcnt(0)
	v_mul_hi_u32 v1, v3, v1
	v_mul_lo_u32 v4, v1, v2
	v_sub_u32_e32 v4, v3, v4
	v_cmp_ge_u32_e32 vcc, v4, v2
	v_add_u32_e32 v5, 1, v1
	s_nop 0
	v_cndmask_b32_e32 v1, v1, v5, vcc
	v_sub_u32_e32 v5, v4, v2
	v_cndmask_b32_e32 v4, v4, v5, vcc
	v_cmp_ge_u32_e32 vcc, v4, v2
	v_add_u32_e32 v4, 1, v1
	s_nop 0
	v_cndmask_b32_e32 v1, v1, v4, vcc
	v_add_u32_e32 v4, 1, v3
	v_mad_u64_u32 v[2:3], s[2:3], v2, v1, v[2:3]
	v_cmp_ne_u32_e32 vcc, v4, v2
	s_and_saveexec_b64 s[2:3], vcc
	s_xor_b64 s[2:3], exec, s[2:3]
	s_movk_i32 s39, 0x7f
	s_cbranch_execz .LBB0_2188
	buffer_inv sc1
	v_mov_b32_e32 v0, s25
	v_add_co_u32_e32 v2, vcc, 0x2000, v0
	v_mov_b32_e32 v0, s24
	s_nop 0
	v_addc_co_u32_e32 v3, vcc, 0, v0, vcc
	flat_load_dword v0, v[2:3] offset:1024 sc1
	s_add_u32 s6, s25, 0x2400
	s_addc_u32 s7, s24, 0
	s_waitcnt vmcnt(0) lgkmcnt(0)
	v_cmp_eq_u32_e32 vcc, v0, v1
	s_and_saveexec_b64 s[4:5], vcc
	s_cbranch_execz .LBB0_2187
	s_mov_b32 s26, 1
	s_mov_b64 s[8:9], 0
	s_branch .LBB0_2179

; __device__ __forceinline__ unsigned xb_ld(unsigned* p)              { return __hip_atomic_load(p, __ATOMIC_RELAXED, __HIP_MEMORY_SCOPE_AGENT); }
; __device__ __forceinline__ unsigned xb_add(unsigned* p, unsigned v) { return __hip_atomic_fetch_add(p, v, __ATOMIC_RELAXED, __HIP_MEMORY_SCOPE_AGENT); }
; #define XB_SPIN(cond, bar) do { unsigned _sp = 0; while (cond) { \
;     if ((++_sp & 255u) == 0u) { if (xb_ld(&(bar)[XB_TMO])) break; if (_sp > XB_SPIN_CAP) { atomicAdd(&(bar)[XB_TMO], 1u); break; } } } } while (0)
; __device__ __forceinline__ void grid_barrier1(int wid_s, unsigned* bar, volatile unsigned* st) {
;     ...
;         const unsigned old = xb_add(&bar[XB_XSUB(x)], 1u);
;         const unsigned gen = old / nloc;
;         if (old + 1u == (gen + 1u) * nloc) {
;     ...
;         } else {
;             XB_SPIN(xb_ld(&bar[XB_XGEN(x)]) == gen, bar);
;             __builtin_amdgcn_fence(__ATOMIC_ACQUIRE, "agent");
.LBB0_2910:
	s_or_b64 exec, exec, s[46:47]
	s_lshl_b32 s2, s33, 8
	s_add_u32 s25, s92, s2
	s_addc_u32 s24, s94, 0
	v_mov_b32_e32 v1, s25
	v_add_co_u32_e32 v4, vcc, 0x1000, v1
	v_mov_b32_e32 v1, s24
	s_nop 0
	v_addc_co_u32_e32 v5, vcc, 0, v1, vcc
	flat_atomic_add v3, v[4:5], v170 offset:1024 sc0
	v_cvt_f32_u32_e32 v1, v2
	v_sub_u32_e32 v4, 0, v2
	v_rcp_iflag_f32_e32 v1, v1
	s_nop 0
	v_mul_f32_e32 v1, 0x4f7ffffe, v1
	v_cvt_u32_f32_e32 v1, v1
	v_mul_lo_u32 v4, v4, v1
	v_mul_hi_u32 v4, v1, v4
	v_add_u32_e32 v1, v1, v4
	s_waitcnt vmcnt(0) lgkmcnt(0)
	v_mul_hi_u32 v1, v3, v1
	v_mul_lo_u32 v4, v1, v2
	v_sub_u32_e32 v4, v3, v4
	v_cmp_ge_u32_e32 vcc, v4, v2
	v_add_u32_e32 v5, 1, v1
	s_nop 0
	v_cndmask_b32_e32 v1, v1, v5, vcc
	v_sub_u32_e32 v5, v4, v2
	v_cndmask_b32_e32 v4, v4, v5, vcc
	v_cmp_ge_u32_e32 vcc, v4, v2
	v_add_u32_e32 v4, 1, v1
	s_nop 0
	v_cndmask_b32_e32 v1, v1, v4, vcc
	v_add_u32_e32 v4, 1, v3
	v_mad_u64_u32 v[2:3], s[2:3], v2, v1, v[2:3]
	v_cmp_ne_u32_e32 vcc, v4, v2
	s_and_saveexec_b64 s[2:3], vcc
	s_xor_b64 s[2:3], exec, s[2:3]
	s_movk_i32 s33, 0x300
	s_cbranch_execz .LBB0_2923
	buffer_inv sc1
	v_mov_b32_e32 v0, s25
	v_add_co_u32_e32 v2, vcc, 0x2000, v0
	v_mov_b32_e32 v0, s24
	s_nop 0
	v_addc_co_u32_e32 v3, vcc, 0, v0, vcc
	flat_load_dword v0, v[2:3] offset:1024 sc1
	s_add_u32 s6, s25, 0x2400
	s_addc_u32 s7, s24, 0
	s_waitcnt vmcnt(0) lgkmcnt(0)
	v_cmp_eq_u32_e32 vcc, v0, v1
	s_and_saveexec_b64 s[4:5], vcc
	s_cbranch_execz .LBB0_2922
	s_mov_b32 s26, 1
	s_mov_b64 s[8:9], 0
	s_branch .LBB0_2914
